# speedup vs baseline: 1.0051x; 1.0051x over previous
; __device__ __forceinline__ float bf2f(unsigned short v) { return __uint_as_float(((unsigned)v) << 16); }
; __device__ __forceinline__ void dsa_tile(const Params& p, unsigned char* smem, int tile) {
;     ...
;         unsigned char* iqs = smem + 8192;
; #pragma unroll
;         for (int i = 0; i < 4; ++i) { const int ch = tid + 512 * i, r = ch >> 7, c = ch & 127;
;             *(u32x4*)(iqs + r * 2048 + ((c ^ r) * 16)) = *(const u32x4*)(projb + (size_t)(q0 + r) * INP + C_IQ + c * 8); }
;         float* wl = (float*)(smem + 40960);
;         if (tid < 256) { const int q = tid & 15, h = tid >> 4; wl[h * 16 + q] = bf2f(projb[(size_t)(q0 + q) * INP + C_IW + h]) * 0.015625f; }
;         __syncthreads();
;         u32x4 yf[16][2];
; #pragma unroll
;         for (int h = 0; h < 16; ++h)
; #pragma unroll
;             for (int ks = 0; ks < 2; ++ks) yf[h][ks] = *(const u32x4*)(iqs + fr * 2048 + (((h * 8 + ks * 4 + fq) ^ fr) * 16));
;         u32x4 chi[2], clo[2];
; #pragma unroll
;         for (int ks = 0; ks < 2; ++ks) {
;             float c[8];
; #pragma unroll
;             for (int e = 0; e < 8; ++e) c[e] = 0.f;
; #pragma unroll
;             for (int h = 0; h < 16; ++h) { const float wh = wl[h * 16 + fr]; float f[8]; unpack8(yf[h][ks], f);
; #pragma unroll
;                 for (int e = 0; e < 8; ++e) c[e] += wh * f[e]; }
.LBB0_287:
	s_or_b64 exec, exec, s[12:13]
	v_bfe_u32 v120, v152, 4, 2
	s_movk_i32 s4, 0x44
	v_bitop3_b32 v65, v120, v153, s4 bitop3:0x36
	s_movk_i32 s4, 0x48
	v_bitop3_b32 v72, v120, v153, s4 bitop3:0x36
	s_movk_i32 s4, 0x4c
	v_bitop3_b32 v73, v120, v153, s4 bitop3:0x36
	s_movk_i32 s4, 0x50
	v_bitop3_b32 v80, v120, v153, s4 bitop3:0x36
	s_movk_i32 s4, 0x54
	v_bitop3_b32 v81, v120, v153, s4 bitop3:0x36
	s_movk_i32 s4, 0x58
	v_bitop3_b32 v88, v120, v153, s4 bitop3:0x36
	s_movk_i32 s4, 0x5c
	v_bitop3_b32 v89, v120, v153, s4 bitop3:0x36
	s_movk_i32 s4, 0x60
	v_bitop3_b32 v96, v120, v153, s4 bitop3:0x36
	s_movk_i32 s4, 0x64
	v_bitop3_b32 v97, v120, v153, s4 bitop3:0x36
	s_movk_i32 s4, 0x68
	v_bitop3_b32 v104, v120, v153, s4 bitop3:0x36
	s_movk_i32 s4, 0x6c
	v_bitop3_b32 v105, v120, v153, s4 bitop3:0x36
	s_movk_i32 s4, 0x70
	v_bitop3_b32 v112, v120, v153, s4 bitop3:0x36
	s_movk_i32 s4, 0x74
	v_bitop3_b32 v113, v120, v153, s4 bitop3:0x36
	s_movk_i32 s4, 0x78
	v_bitop3_b32 v122, v120, v153, s4 bitop3:0x36
	s_movk_i32 s4, 0x7c
	v_lshl_add_u32 v121, v153, 11, 0
	v_xor_b32_e32 v0, v120, v153
	v_bitop3_b32 v1, v120, v153, 4 bitop3:0x36
	v_bitop3_b32 v8, v120, v153, 8 bitop3:0x36
	v_bitop3_b32 v9, v120, v153, 12 bitop3:0x36
	v_bitop3_b32 v16, v120, v153, 16 bitop3:0x36
	v_bitop3_b32 v17, v120, v153, 20 bitop3:0x36
	v_bitop3_b32 v24, v120, v153, 24 bitop3:0x36
	v_bitop3_b32 v25, v120, v153, 28 bitop3:0x36
	v_bitop3_b32 v32, v120, v153, 32 bitop3:0x36
	v_bitop3_b32 v33, v120, v153, 36 bitop3:0x36
	v_bitop3_b32 v40, v120, v153, 40 bitop3:0x36
	v_bitop3_b32 v41, v120, v153, 44 bitop3:0x36
	v_bitop3_b32 v48, v120, v153, 48 bitop3:0x36
	v_bitop3_b32 v49, v120, v153, 52 bitop3:0x36
	v_bitop3_b32 v56, v120, v153, 56 bitop3:0x36
	v_bitop3_b32 v57, v120, v153, 60 bitop3:0x36
	v_bitop3_b32 v64, v120, v153, 64 bitop3:0x36
	v_bitop3_b32 v120, v120, v153, s4 bitop3:0x36
	v_lshl_add_u32 v154, v153, 2, 0
	v_lshl_add_u32 v0, v0, 4, v121
	v_lshl_add_u32 v4, v1, 4, v121
	v_lshl_add_u32 v8, v8, 4, v121
	v_lshl_add_u32 v12, v9, 4, v121
	v_lshl_add_u32 v16, v16, 4, v121
	v_lshl_add_u32 v20, v17, 4, v121
	v_lshl_add_u32 v24, v24, 4, v121
	v_lshl_add_u32 v28, v25, 4, v121
	v_lshl_add_u32 v32, v32, 4, v121
	v_lshl_add_u32 v36, v33, 4, v121
	v_lshl_add_u32 v40, v40, 4, v121
	v_lshl_add_u32 v44, v41, 4, v121
	v_lshl_add_u32 v48, v48, 4, v121
	v_lshl_add_u32 v52, v49, 4, v121
	v_lshl_add_u32 v56, v56, 4, v121
	v_lshl_add_u32 v60, v57, 4, v121
	v_lshl_add_u32 v64, v64, 4, v121
	v_lshl_add_u32 v68, v65, 4, v121
	v_lshl_add_u32 v72, v72, 4, v121
	v_lshl_add_u32 v76, v73, 4, v121
	v_lshl_add_u32 v80, v80, 4, v121
	v_lshl_add_u32 v84, v81, 4, v121
	v_lshl_add_u32 v88, v88, 4, v121
	v_lshl_add_u32 v92, v89, 4, v121
	v_lshl_add_u32 v96, v96, 4, v121
	v_lshl_add_u32 v100, v97, 4, v121
	v_lshl_add_u32 v104, v104, 4, v121
	v_lshl_add_u32 v108, v105, 4, v121
	v_lshl_add_u32 v112, v112, 4, v121
	v_lshl_add_u32 v116, v113, 4, v121
	v_lshl_add_u32 v122, v122, 4, v121
	v_lshl_add_u32 v124, v120, 4, v121
	v_add_u32_e32 v155, 0xa000, v154
	s_waitcnt lgkmcnt(0)
	s_barrier
	ds_read_b128 v[0:3], v0 offset:8192
	ds_read_b128 v[4:7], v4 offset:8192
	ds_read_b128 v[8:11], v8 offset:8192
	ds_read_b128 v[12:15], v12 offset:8192
	ds_read_b128 v[16:19], v16 offset:8192
	ds_read_b128 v[20:23], v20 offset:8192
	ds_read_b128 v[24:27], v24 offset:8192
	ds_read_b128 v[28:31], v28 offset:8192
	ds_read_b128 v[32:35], v32 offset:8192
	ds_read_b128 v[36:39], v36 offset:8192
	ds_read_b128 v[40:43], v40 offset:8192
	ds_read_b128 v[44:47], v44 offset:8192
	ds_read_b128 v[48:51], v48 offset:8192
	ds_read_b128 v[52:55], v52 offset:8192
	ds_read_b128 v[56:59], v56 offset:8192
	ds_read_b128 v[60:63], v60 offset:8192
	ds_read_b128 v[64:67], v64 offset:8192
	ds_read_b128 v[68:71], v68 offset:8192
	ds_read_b128 v[72:75], v72 offset:8192
	ds_read_b128 v[76:79], v76 offset:8192
	ds_read_b128 v[80:83], v80 offset:8192
	ds_read_b128 v[84:87], v84 offset:8192
	ds_read_b128 v[88:91], v88 offset:8192
	ds_read_b128 v[92:95], v92 offset:8192
	ds_read_b128 v[96:99], v96 offset:8192
	ds_read_b128 v[100:103], v100 offset:8192
	ds_read_b128 v[104:107], v104 offset:8192
	ds_read_b128 v[108:111], v108 offset:8192
	ds_read_b128 v[112:115], v112 offset:8192
	ds_read_b128 v[116:119], v116 offset:8192
	ds_read_b128 v[120:123], v122 offset:8192
	ds_read_b128 v[124:127], v124 offset:8192
	ds_read2_b32 v[128:129], v155 offset1:16
	s_waitcnt lgkmcnt(14)
	v_lshlrev_b32_e32 v130, 16, v0
	v_and_b32_e32 v131, 0xffff0000, v0
	v_lshlrev_b32_e32 v132, 16, v1
	v_and_b32_e32 v133, 0xffff0000, v1
	v_lshlrev_b32_e32 v134, 16, v2
	v_and_b32_e32 v135, 0xffff0000, v2
	v_lshlrev_b32_e32 v136, 16, v3
	v_and_b32_e32 v137, 0xffff0000, v3
	s_waitcnt lgkmcnt(0)
	v_fma_f32 v138, v128, v130, 0
	v_fma_f32 v139, v128, v131, 0
	v_fma_f32 v132, v128, v132, 0
	v_fma_f32 v133, v128, v133, 0
	v_fma_f32 v134, v128, v134, 0
	v_fma_f32 v135, v128, v135, 0
	v_fma_f32 v136, v128, v136, 0
	v_fma_f32 v137, v128, v137, 0
	v_lshlrev_b32_e32 v128, 16, v8
	v_and_b32_e32 v130, 0xffff0000, v8
	v_lshlrev_b32_e32 v131, 16, v9
	v_and_b32_e32 v140, 0xffff0000, v9
	v_lshlrev_b32_e32 v141, 16, v10
	v_and_b32_e32 v142, 0xffff0000, v10
	v_lshlrev_b32_e32 v143, 16, v11
	v_and_b32_e32 v144, 0xffff0000, v11
	v_fmac_f32_e32 v138, v129, v128
	v_fmac_f32_e32 v139, v129, v130
	v_fmac_f32_e32 v132, v129, v131
	v_fmac_f32_e32 v133, v129, v140
	v_fmac_f32_e32 v134, v129, v141
	v_fmac_f32_e32 v135, v129, v142
	v_fmac_f32_e32 v136, v129, v143
	v_fmac_f32_e32 v137, v129, v144
	ds_read2_b32 v[128:129], v155 offset0:32 offset1:48
	v_lshlrev_b32_e32 v130, 16, v16
	v_and_b32_e32 v131, 0xffff0000, v16
	v_lshlrev_b32_e32 v140, 16, v17
	v_and_b32_e32 v141, 0xffff0000, v17
	v_lshlrev_b32_e32 v142, 16, v18
	v_and_b32_e32 v143, 0xffff0000, v18
	v_lshlrev_b32_e32 v144, 16, v19
	v_and_b32_e32 v145, 0xffff0000, v19
	s_waitcnt lgkmcnt(0)
; __device__ __forceinline__ void dsa_tile(const Params& p, unsigned char* smem, int tile) {
;     ...
;             for (int h = 0; h < 16; ++h) { const float wh = wl[h * 16 + fr]; float f[8]; unpack8(yf[h][ks], f);
; #pragma unroll
;                 for (int e = 0; e < 8; ++e) c[e] += wh * f[e]; }
	v_fmac_f32_e32 v138, v128, v130
	v_fmac_f32_e32 v139, v128, v131
	v_fmac_f32_e32 v132, v128, v140
	v_fmac_f32_e32 v133, v128, v141
	v_fmac_f32_e32 v134, v128, v142
	v_fmac_f32_e32 v135, v128, v143
	v_fmac_f32_e32 v136, v128, v144
	v_fmac_f32_e32 v137, v128, v145
	v_lshlrev_b32_e32 v128, 16, v24
	v_and_b32_e32 v130, 0xffff0000, v24
	v_lshlrev_b32_e32 v131, 16, v25
	v_and_b32_e32 v140, 0xffff0000, v25
	v_lshlrev_b32_e32 v141, 16, v26
	v_and_b32_e32 v142, 0xffff0000, v26
	v_lshlrev_b32_e32 v143, 16, v27
	v_and_b32_e32 v144, 0xffff0000, v27
	v_fmac_f32_e32 v138, v129, v128
	v_fmac_f32_e32 v139, v129, v130
	v_fmac_f32_e32 v132, v129, v131
	v_fmac_f32_e32 v133, v129, v140
	v_fmac_f32_e32 v134, v129, v141
	v_fmac_f32_e32 v135, v129, v142
	v_fmac_f32_e32 v136, v129, v143
	v_fmac_f32_e32 v137, v129, v144
	ds_read2_b32 v[128:129], v155 offset0:64 offset1:80
	v_lshlrev_b32_e32 v130, 16, v32
	v_and_b32_e32 v131, 0xffff0000, v32
	v_lshlrev_b32_e32 v140, 16, v33
	v_and_b32_e32 v141, 0xffff0000, v33
	v_lshlrev_b32_e32 v142, 16, v34
	v_and_b32_e32 v143, 0xffff0000, v34
	v_lshlrev_b32_e32 v144, 16, v35
	v_and_b32_e32 v145, 0xffff0000, v35
	s_waitcnt lgkmcnt(0)
	v_fmac_f32_e32 v138, v128, v130
	v_fmac_f32_e32 v139, v128, v131
	v_fmac_f32_e32 v132, v128, v140
	v_fmac_f32_e32 v133, v128, v141
	v_fmac_f32_e32 v134, v128, v142
	v_fmac_f32_e32 v135, v128, v143
	v_fmac_f32_e32 v136, v128, v144
	v_fmac_f32_e32 v137, v128, v145
	v_lshlrev_b32_e32 v128, 16, v40
	v_and_b32_e32 v130, 0xffff0000, v40
	v_lshlrev_b32_e32 v131, 16, v41
	v_and_b32_e32 v140, 0xffff0000, v41
	v_lshlrev_b32_e32 v141, 16, v42
	v_and_b32_e32 v142, 0xffff0000, v42
	v_lshlrev_b32_e32 v143, 16, v43
	v_and_b32_e32 v144, 0xffff0000, v43
	v_fmac_f32_e32 v138, v129, v128
	v_fmac_f32_e32 v139, v129, v130
	v_fmac_f32_e32 v132, v129, v131
	v_fmac_f32_e32 v133, v129, v140
	v_fmac_f32_e32 v134, v129, v141
	v_fmac_f32_e32 v135, v129, v142
	v_fmac_f32_e32 v136, v129, v143
	v_fmac_f32_e32 v137, v129, v144
	ds_read2_b32 v[128:129], v155 offset0:96 offset1:112
	v_lshlrev_b32_e32 v130, 16, v48
	v_and_b32_e32 v131, 0xffff0000, v48
	v_lshlrev_b32_e32 v140, 16, v49
	v_and_b32_e32 v141, 0xffff0000, v49
	v_lshlrev_b32_e32 v142, 16, v50
	v_and_b32_e32 v143, 0xffff0000, v50
	v_lshlrev_b32_e32 v144, 16, v51
	v_and_b32_e32 v145, 0xffff0000, v51
	s_waitcnt lgkmcnt(0)
	v_fmac_f32_e32 v138, v128, v130
	v_fmac_f32_e32 v139, v128, v131
	v_fmac_f32_e32 v132, v128, v140
	v_fmac_f32_e32 v133, v128, v141
	v_fmac_f32_e32 v134, v128, v142
	v_fmac_f32_e32 v135, v128, v143
	v_fmac_f32_e32 v136, v128, v144
	v_fmac_f32_e32 v137, v128, v145
	v_lshlrev_b32_e32 v128, 16, v56
	v_and_b32_e32 v130, 0xffff0000, v56
	v_lshlrev_b32_e32 v131, 16, v57
	v_and_b32_e32 v140, 0xffff0000, v57
	v_lshlrev_b32_e32 v141, 16, v58
	v_and_b32_e32 v142, 0xffff0000, v58
	v_lshlrev_b32_e32 v143, 16, v59
	v_and_b32_e32 v144, 0xffff0000, v59
	v_fmac_f32_e32 v138, v129, v128
	v_fmac_f32_e32 v139, v129, v130
	v_fmac_f32_e32 v132, v129, v131
	v_fmac_f32_e32 v133, v129, v140
	v_fmac_f32_e32 v134, v129, v141
	v_fmac_f32_e32 v135, v129, v142
	v_fmac_f32_e32 v136, v129, v143
	v_fmac_f32_e32 v137, v129, v144
	ds_read2_b32 v[128:129], v155 offset0:128 offset1:144
	v_lshlrev_b32_e32 v130, 16, v64
	v_and_b32_e32 v131, 0xffff0000, v64
	v_lshlrev_b32_e32 v140, 16, v65
	v_and_b32_e32 v141, 0xffff0000, v65
	v_lshlrev_b32_e32 v142, 16, v66
	v_and_b32_e32 v143, 0xffff0000, v66
	v_lshlrev_b32_e32 v144, 16, v67
	v_and_b32_e32 v145, 0xffff0000, v67
	s_waitcnt lgkmcnt(0)
	v_fmac_f32_e32 v138, v128, v130
	v_fmac_f32_e32 v139, v128, v131
	v_fmac_f32_e32 v132, v128, v140
	v_fmac_f32_e32 v133, v128, v141
	v_fmac_f32_e32 v134, v128, v142
	v_fmac_f32_e32 v135, v128, v143
	v_fmac_f32_e32 v136, v128, v144
	v_fmac_f32_e32 v137, v128, v145
	v_lshlrev_b32_e32 v128, 16, v72
	v_and_b32_e32 v130, 0xffff0000, v72
	v_lshlrev_b32_e32 v131, 16, v73
	v_and_b32_e32 v140, 0xffff0000, v73
	v_lshlrev_b32_e32 v141, 16, v74
	v_and_b32_e32 v142, 0xffff0000, v74
	v_lshlrev_b32_e32 v143, 16, v75
	v_and_b32_e32 v144, 0xffff0000, v75
	v_fmac_f32_e32 v138, v129, v128
	v_fmac_f32_e32 v139, v129, v130
	v_fmac_f32_e32 v132, v129, v131
	v_fmac_f32_e32 v133, v129, v140
	v_fmac_f32_e32 v134, v129, v141
	v_fmac_f32_e32 v135, v129, v142
	v_fmac_f32_e32 v136, v129, v143
	v_fmac_f32_e32 v137, v129, v144
	ds_read2_b32 v[128:129], v155 offset0:160 offset1:176
	v_lshlrev_b32_e32 v130, 16, v80
	v_and_b32_e32 v131, 0xffff0000, v80
	v_lshlrev_b32_e32 v140, 16, v81
	v_and_b32_e32 v141, 0xffff0000, v81
	v_lshlrev_b32_e32 v142, 16, v82
	v_and_b32_e32 v143, 0xffff0000, v82
	v_lshlrev_b32_e32 v144, 16, v83
	v_and_b32_e32 v145, 0xffff0000, v83
	s_waitcnt lgkmcnt(0)
	v_fmac_f32_e32 v138, v128, v130
	v_fmac_f32_e32 v139, v128, v131
	v_fmac_f32_e32 v132, v128, v140
	v_fmac_f32_e32 v133, v128, v141
	v_fmac_f32_e32 v134, v128, v142
	v_fmac_f32_e32 v135, v128, v143
	v_fmac_f32_e32 v136, v128, v144
	v_fmac_f32_e32 v137, v128, v145
	v_lshlrev_b32_e32 v128, 16, v88
	v_and_b32_e32 v130, 0xffff0000, v88
	v_lshlrev_b32_e32 v131, 16, v89
	v_and_b32_e32 v140, 0xffff0000, v89
	v_lshlrev_b32_e32 v141, 16, v90
	v_and_b32_e32 v142, 0xffff0000, v90
	v_lshlrev_b32_e32 v143, 16, v91
	v_and_b32_e32 v144, 0xffff0000, v91
	v_fmac_f32_e32 v138, v129, v128
	v_fmac_f32_e32 v139, v129, v130
	v_fmac_f32_e32 v132, v129, v131
	v_fmac_f32_e32 v133, v129, v140
	v_fmac_f32_e32 v134, v129, v141
	v_fmac_f32_e32 v135, v129, v142
	v_fmac_f32_e32 v136, v129, v143
	v_fmac_f32_e32 v137, v129, v144
	ds_read2_b32 v[128:129], v155 offset0:192 offset1:208
	v_lshlrev_b32_e32 v130, 16, v96
	v_and_b32_e32 v131, 0xffff0000, v96
	v_lshlrev_b32_e32 v140, 16, v97
	v_and_b32_e32 v141, 0xffff0000, v97
	v_lshlrev_b32_e32 v142, 16, v98
	v_and_b32_e32 v143, 0xffff0000, v98
	v_lshlrev_b32_e32 v144, 16, v99
	v_and_b32_e32 v145, 0xffff0000, v99
	s_waitcnt lgkmcnt(0)
; __device__ __forceinline__ void dsa_tile(const Params& p, unsigned char* smem, int tile) {
;     ...
;             for (int h = 0; h < 16; ++h) { const float wh = wl[h * 16 + fr]; float f[8]; unpack8(yf[h][ks], f);
; #pragma unroll
;                 for (int e = 0; e < 8; ++e) c[e] += wh * f[e]; }
;             chi[ks] = pack8(c);
;             float fh[8]; unpack8(chi[ks], fh);
; #pragma unroll
;             for (int e = 0; e < 8; ++e) c[e] -= fh[e];
;             clo[ks] = pack8(c);
	v_fmac_f32_e32 v138, v128, v130
	v_fmac_f32_e32 v139, v128, v131
	v_fmac_f32_e32 v132, v128, v140
	v_fmac_f32_e32 v133, v128, v141
	v_fmac_f32_e32 v134, v128, v142
	v_fmac_f32_e32 v135, v128, v143
	v_fmac_f32_e32 v136, v128, v144
	v_fmac_f32_e32 v137, v128, v145
	v_lshlrev_b32_e32 v128, 16, v104
	v_and_b32_e32 v130, 0xffff0000, v104
	v_lshlrev_b32_e32 v131, 16, v105
	v_and_b32_e32 v140, 0xffff0000, v105
	v_lshlrev_b32_e32 v141, 16, v106
	v_and_b32_e32 v142, 0xffff0000, v106
	v_lshlrev_b32_e32 v143, 16, v107
	v_and_b32_e32 v144, 0xffff0000, v107
	v_fmac_f32_e32 v138, v129, v128
	v_fmac_f32_e32 v139, v129, v130
	v_fmac_f32_e32 v132, v129, v131
	v_fmac_f32_e32 v133, v129, v140
	v_fmac_f32_e32 v134, v129, v141
	v_fmac_f32_e32 v135, v129, v142
	v_fmac_f32_e32 v136, v129, v143
	v_fmac_f32_e32 v137, v129, v144
	ds_read2_b32 v[128:129], v155 offset0:224 offset1:240
	v_lshlrev_b32_e32 v130, 16, v112
	v_and_b32_e32 v131, 0xffff0000, v112
	v_lshlrev_b32_e32 v140, 16, v113
	v_and_b32_e32 v141, 0xffff0000, v113
	v_lshlrev_b32_e32 v142, 16, v114
	v_and_b32_e32 v143, 0xffff0000, v114
	v_lshlrev_b32_e32 v144, 16, v115
	v_and_b32_e32 v145, 0xffff0000, v115
	s_waitcnt lgkmcnt(0)
	v_fmac_f32_e32 v138, v128, v130
	v_fmac_f32_e32 v139, v128, v131
	v_fmac_f32_e32 v132, v128, v140
	v_fmac_f32_e32 v133, v128, v141
	v_fmac_f32_e32 v134, v128, v142
	v_fmac_f32_e32 v135, v128, v143
	v_fmac_f32_e32 v136, v128, v144
	v_fmac_f32_e32 v137, v128, v145
	v_lshlrev_b32_e32 v128, 16, v120
	v_and_b32_e32 v130, 0xffff0000, v120
	v_lshlrev_b32_e32 v131, 16, v121
	v_and_b32_e32 v140, 0xffff0000, v121
	v_lshlrev_b32_e32 v141, 16, v122
	v_and_b32_e32 v142, 0xffff0000, v122
	v_lshlrev_b32_e32 v143, 16, v123
	v_and_b32_e32 v144, 0xffff0000, v123
	v_fmac_f32_e32 v138, v129, v128
	v_fmac_f32_e32 v139, v129, v130
	v_fmac_f32_e32 v132, v129, v131
	v_fmac_f32_e32 v133, v129, v140
	v_fmac_f32_e32 v134, v129, v141
	v_fmac_f32_e32 v135, v129, v142
	v_fmac_f32_e32 v136, v129, v143
	v_fmac_f32_e32 v137, v129, v144
	v_cvt_pk_bf16_f32 v128, v138, v139
	v_cvt_pk_bf16_f32 v129, v132, v133
	v_cvt_pk_bf16_f32 v130, v134, v135
	v_cvt_pk_bf16_f32 v131, v136, v137
	v_and_b32_e32 v148, 0xffff0000, v13
	v_and_b32_e32 v143, 0xffff0000, v129
	v_lshlrev_b32_e32 v144, 16, v130
	v_and_b32_e32 v145, 0xffff0000, v130
	v_lshlrev_b32_e32 v146, 16, v131
	v_and_b32_e32 v147, 0xffff0000, v131
	v_lshlrev_b32_e32 v140, 16, v128
	v_and_b32_e32 v141, 0xffff0000, v128
	v_lshlrev_b32_e32 v142, 16, v129
	v_sub_f32_e32 v133, v133, v143
	v_sub_f32_e32 v134, v134, v144
	v_sub_f32_e32 v135, v135, v145
	v_sub_f32_e32 v136, v136, v146
	v_sub_f32_e32 v137, v137, v147
	v_sub_f32_e32 v138, v138, v140
	v_sub_f32_e32 v139, v139, v141
	v_sub_f32_e32 v140, v132, v142
	v_cvt_pk_bf16_f32 v132, v138, v139
	v_cvt_pk_bf16_f32 v133, v140, v133
	v_cvt_pk_bf16_f32 v134, v134, v135
	v_cvt_pk_bf16_f32 v135, v136, v137
	ds_read2_b32 v[136:137], v155 offset1:16
	v_lshlrev_b32_e32 v138, 16, v4
	v_and_b32_e32 v139, 0xffff0000, v4
	v_lshlrev_b32_e32 v140, 16, v5
	v_and_b32_e32 v141, 0xffff0000, v5
	v_lshlrev_b32_e32 v142, 16, v6
	v_and_b32_e32 v143, 0xffff0000, v6
	v_lshlrev_b32_e32 v144, 16, v7
	v_and_b32_e32 v145, 0xffff0000, v7
	s_waitcnt lgkmcnt(0)
	v_fma_f32 v146, v136, v138, 0
	v_fma_f32 v147, v136, v139, 0
	v_fma_f32 v140, v136, v140, 0
	v_fma_f32 v141, v136, v141, 0
	v_fma_f32 v142, v136, v142, 0
	v_fma_f32 v143, v136, v143, 0
	v_fma_f32 v144, v136, v144, 0
	v_fma_f32 v145, v136, v145, 0
	v_lshlrev_b32_e32 v136, 16, v12
	v_and_b32_e32 v138, 0xffff0000, v12
	v_lshlrev_b32_e32 v139, 16, v13
	v_lshlrev_b32_e32 v149, 16, v14
	v_and_b32_e32 v150, 0xffff0000, v14
	v_lshlrev_b32_e32 v151, 16, v15
	v_and_b32_e32 v156, 0xffff0000, v15
	v_fmac_f32_e32 v146, v137, v136
	v_fmac_f32_e32 v147, v137, v138
	v_fmac_f32_e32 v140, v137, v139
	v_fmac_f32_e32 v141, v137, v148
	v_fmac_f32_e32 v142, v137, v149
	v_fmac_f32_e32 v143, v137, v150
	v_fmac_f32_e32 v144, v137, v151
	v_fmac_f32_e32 v145, v137, v156
	ds_read2_b32 v[136:137], v155 offset0:32 offset1:48
	v_lshlrev_b32_e32 v138, 16, v20
	v_and_b32_e32 v139, 0xffff0000, v20
	v_lshlrev_b32_e32 v148, 16, v21
	v_and_b32_e32 v149, 0xffff0000, v21
	v_lshlrev_b32_e32 v150, 16, v22
	v_and_b32_e32 v151, 0xffff0000, v22
	v_lshlrev_b32_e32 v156, 16, v23
	v_and_b32_e32 v157, 0xffff0000, v23
	s_waitcnt lgkmcnt(0)
	v_fmac_f32_e32 v146, v136, v138
	v_fmac_f32_e32 v147, v136, v139
	v_fmac_f32_e32 v140, v136, v148
	v_fmac_f32_e32 v141, v136, v149
	v_fmac_f32_e32 v142, v136, v150
	v_fmac_f32_e32 v143, v136, v151
	v_fmac_f32_e32 v144, v136, v156
	v_fmac_f32_e32 v145, v136, v157
	v_lshlrev_b32_e32 v136, 16, v28
	v_and_b32_e32 v138, 0xffff0000, v28
	v_lshlrev_b32_e32 v139, 16, v29
	v_and_b32_e32 v148, 0xffff0000, v29
	v_lshlrev_b32_e32 v149, 16, v30
	v_and_b32_e32 v150, 0xffff0000, v30
	v_lshlrev_b32_e32 v151, 16, v31
	v_and_b32_e32 v156, 0xffff0000, v31
	v_fmac_f32_e32 v146, v137, v136
	v_fmac_f32_e32 v147, v137, v138
	v_fmac_f32_e32 v140, v137, v139
	v_fmac_f32_e32 v141, v137, v148
	v_fmac_f32_e32 v142, v137, v149
	v_fmac_f32_e32 v143, v137, v150
	v_fmac_f32_e32 v144, v137, v151
	v_fmac_f32_e32 v145, v137, v156
	ds_read2_b32 v[136:137], v155 offset0:64 offset1:80
	v_lshlrev_b32_e32 v138, 16, v36
	v_and_b32_e32 v139, 0xffff0000, v36
	v_lshlrev_b32_e32 v148, 16, v37
	v_and_b32_e32 v149, 0xffff0000, v37
	v_lshlrev_b32_e32 v150, 16, v38
	v_and_b32_e32 v151, 0xffff0000, v38
	v_lshlrev_b32_e32 v156, 16, v39
	v_and_b32_e32 v157, 0xffff0000, v39
	s_waitcnt lgkmcnt(0)
; __device__ __forceinline__ void dsa_tile(const Params& p, unsigned char* smem, int tile) {
;     ...
;             for (int h = 0; h < 16; ++h) { const float wh = wl[h * 16 + fr]; float f[8]; unpack8(yf[h][ks], f);
; #pragma unroll
;                 for (int e = 0; e < 8; ++e) c[e] += wh * f[e]; }
	v_fmac_f32_e32 v146, v136, v138
	v_fmac_f32_e32 v147, v136, v139
	v_fmac_f32_e32 v140, v136, v148
	v_fmac_f32_e32 v141, v136, v149
	v_fmac_f32_e32 v142, v136, v150
	v_fmac_f32_e32 v143, v136, v151
	v_fmac_f32_e32 v144, v136, v156
	v_fmac_f32_e32 v145, v136, v157
	v_lshlrev_b32_e32 v136, 16, v44
	v_and_b32_e32 v138, 0xffff0000, v44
	v_lshlrev_b32_e32 v139, 16, v45
	v_and_b32_e32 v148, 0xffff0000, v45
	v_lshlrev_b32_e32 v149, 16, v46
	v_and_b32_e32 v150, 0xffff0000, v46
	v_lshlrev_b32_e32 v151, 16, v47
	v_and_b32_e32 v156, 0xffff0000, v47
	v_fmac_f32_e32 v146, v137, v136
	v_fmac_f32_e32 v147, v137, v138
	v_fmac_f32_e32 v140, v137, v139
	v_fmac_f32_e32 v141, v137, v148
	v_fmac_f32_e32 v142, v137, v149
	v_fmac_f32_e32 v143, v137, v150
	v_fmac_f32_e32 v144, v137, v151
	v_fmac_f32_e32 v145, v137, v156
	ds_read2_b32 v[136:137], v155 offset0:96 offset1:112
	v_lshlrev_b32_e32 v138, 16, v52
	v_and_b32_e32 v139, 0xffff0000, v52
	v_lshlrev_b32_e32 v148, 16, v53
	v_and_b32_e32 v149, 0xffff0000, v53
	v_lshlrev_b32_e32 v150, 16, v54
	v_and_b32_e32 v151, 0xffff0000, v54
	v_lshlrev_b32_e32 v156, 16, v55
	v_and_b32_e32 v157, 0xffff0000, v55
	s_waitcnt lgkmcnt(0)
	v_fmac_f32_e32 v146, v136, v138
	v_fmac_f32_e32 v147, v136, v139
	v_fmac_f32_e32 v140, v136, v148
	v_fmac_f32_e32 v141, v136, v149
	v_fmac_f32_e32 v142, v136, v150
	v_fmac_f32_e32 v143, v136, v151
	v_fmac_f32_e32 v144, v136, v156
	v_fmac_f32_e32 v145, v136, v157
	v_lshlrev_b32_e32 v136, 16, v60
	v_and_b32_e32 v138, 0xffff0000, v60
	v_lshlrev_b32_e32 v139, 16, v61
	v_and_b32_e32 v148, 0xffff0000, v61
	v_lshlrev_b32_e32 v149, 16, v62
	v_and_b32_e32 v150, 0xffff0000, v62
	v_lshlrev_b32_e32 v151, 16, v63
	v_and_b32_e32 v156, 0xffff0000, v63
	v_fmac_f32_e32 v146, v137, v136
	v_fmac_f32_e32 v147, v137, v138
	v_fmac_f32_e32 v140, v137, v139
	v_fmac_f32_e32 v141, v137, v148
	v_fmac_f32_e32 v142, v137, v149
	v_fmac_f32_e32 v143, v137, v150
	v_fmac_f32_e32 v144, v137, v151
	v_fmac_f32_e32 v145, v137, v156
	ds_read2_b32 v[136:137], v155 offset0:128 offset1:144
	v_lshlrev_b32_e32 v138, 16, v68
	v_and_b32_e32 v139, 0xffff0000, v68
	v_lshlrev_b32_e32 v148, 16, v69
	v_and_b32_e32 v149, 0xffff0000, v69
	v_lshlrev_b32_e32 v150, 16, v70
	v_and_b32_e32 v151, 0xffff0000, v70
	v_lshlrev_b32_e32 v156, 16, v71
	v_and_b32_e32 v157, 0xffff0000, v71
	s_waitcnt lgkmcnt(0)
	v_fmac_f32_e32 v146, v136, v138
	v_fmac_f32_e32 v147, v136, v139
	v_fmac_f32_e32 v140, v136, v148
	v_fmac_f32_e32 v141, v136, v149
	v_fmac_f32_e32 v142, v136, v150
	v_fmac_f32_e32 v143, v136, v151
	v_fmac_f32_e32 v144, v136, v156
	v_fmac_f32_e32 v145, v136, v157
	v_lshlrev_b32_e32 v136, 16, v76
	v_and_b32_e32 v138, 0xffff0000, v76
	v_lshlrev_b32_e32 v139, 16, v77
	v_and_b32_e32 v148, 0xffff0000, v77
	v_lshlrev_b32_e32 v149, 16, v78
	v_and_b32_e32 v150, 0xffff0000, v78
	v_lshlrev_b32_e32 v151, 16, v79
	v_and_b32_e32 v156, 0xffff0000, v79
	v_fmac_f32_e32 v146, v137, v136
	v_fmac_f32_e32 v147, v137, v138
	v_fmac_f32_e32 v140, v137, v139
	v_fmac_f32_e32 v141, v137, v148
	v_fmac_f32_e32 v142, v137, v149
	v_fmac_f32_e32 v143, v137, v150
	v_fmac_f32_e32 v144, v137, v151
	v_fmac_f32_e32 v145, v137, v156
	ds_read2_b32 v[136:137], v155 offset0:160 offset1:176
	v_lshlrev_b32_e32 v138, 16, v84
	v_and_b32_e32 v139, 0xffff0000, v84
	v_lshlrev_b32_e32 v148, 16, v85
	v_and_b32_e32 v149, 0xffff0000, v85
	v_lshlrev_b32_e32 v150, 16, v86
	v_and_b32_e32 v151, 0xffff0000, v86
	v_lshlrev_b32_e32 v156, 16, v87
	v_and_b32_e32 v157, 0xffff0000, v87
	s_waitcnt lgkmcnt(0)
	v_fmac_f32_e32 v146, v136, v138
	v_fmac_f32_e32 v147, v136, v139
	v_fmac_f32_e32 v140, v136, v148
	v_fmac_f32_e32 v141, v136, v149
	v_fmac_f32_e32 v142, v136, v150
	v_fmac_f32_e32 v143, v136, v151
	v_fmac_f32_e32 v144, v136, v156
	v_fmac_f32_e32 v145, v136, v157
	v_lshlrev_b32_e32 v136, 16, v92
	v_and_b32_e32 v138, 0xffff0000, v92
	v_lshlrev_b32_e32 v139, 16, v93
	v_and_b32_e32 v148, 0xffff0000, v93
	v_lshlrev_b32_e32 v149, 16, v94
	v_and_b32_e32 v150, 0xffff0000, v94
	v_lshlrev_b32_e32 v151, 16, v95
	v_and_b32_e32 v156, 0xffff0000, v95
	v_fmac_f32_e32 v146, v137, v136
	v_fmac_f32_e32 v147, v137, v138
	v_fmac_f32_e32 v140, v137, v139
	v_fmac_f32_e32 v141, v137, v148
	v_fmac_f32_e32 v142, v137, v149
	v_fmac_f32_e32 v143, v137, v150
	v_fmac_f32_e32 v144, v137, v151
	v_fmac_f32_e32 v145, v137, v156
	ds_read2_b32 v[136:137], v155 offset0:192 offset1:208
	v_lshlrev_b32_e32 v138, 16, v100
	v_and_b32_e32 v139, 0xffff0000, v100
	v_lshlrev_b32_e32 v148, 16, v101
	v_and_b32_e32 v149, 0xffff0000, v101
	v_lshlrev_b32_e32 v150, 16, v102
	v_and_b32_e32 v151, 0xffff0000, v102
	v_lshlrev_b32_e32 v156, 16, v103
	v_and_b32_e32 v157, 0xffff0000, v103
	s_waitcnt lgkmcnt(0)
; __device__ __forceinline__ void dsa_tile(const Params& p, unsigned char* smem, int tile) {
;     ...
;             chi[ks] = pack8(c);
;             float fh[8]; unpack8(chi[ks], fh);
; #pragma unroll
;             for (int e = 0; e < 8; ++e) c[e] -= fh[e];
;             clo[ks] = pack8(c);
;         }
;         float wv[16];
; #pragma unroll
;         for (int h = 0; h < 16; ++h) wv[h] = wl[h * 16 + fr];
;         const int nkb = qt + 1;
;         const bf16_t* kbase = (const bf16_t*)(p.ws + WS_IKC) + (size_t)b * SEQ * 64 + lane * 8;
;         int kb = wid;
;         u32x4 x0 = {0u, 0u, 0u, 0u}, x1 = x0;
;         if (kb < nkb) { const bf16_t* kr = kbase + (size_t)kb * 16 * 64; x0 = *(const u32x4*)kr; x1 = *(const u32x4*)(kr + 512); }
;         for (; kb < nkb; kb += 8) {
;             const int kn = (kb + 8 < nkb) ? kb + 8 : kb;
;             const bf16_t* kr = kbase + (size_t)kn * 16 * 64;
;             const u32x4 nx0 = *(const u32x4*)kr, nx1 = *(const u32x4*)(kr + 512);
	v_fmac_f32_e32 v146, v136, v138
	v_fmac_f32_e32 v147, v136, v139
	v_fmac_f32_e32 v140, v136, v148
	v_fmac_f32_e32 v141, v136, v149
	v_fmac_f32_e32 v142, v136, v150
	v_fmac_f32_e32 v143, v136, v151
	v_fmac_f32_e32 v144, v136, v156
	v_fmac_f32_e32 v145, v136, v157
	v_lshlrev_b32_e32 v136, 16, v108
	v_and_b32_e32 v138, 0xffff0000, v108
	v_lshlrev_b32_e32 v139, 16, v109
	v_and_b32_e32 v148, 0xffff0000, v109
	v_lshlrev_b32_e32 v149, 16, v110
	v_and_b32_e32 v150, 0xffff0000, v110
	v_lshlrev_b32_e32 v151, 16, v111
	v_and_b32_e32 v156, 0xffff0000, v111
	v_fmac_f32_e32 v146, v137, v136
	v_fmac_f32_e32 v147, v137, v138
	v_fmac_f32_e32 v140, v137, v139
	v_fmac_f32_e32 v141, v137, v148
	v_fmac_f32_e32 v142, v137, v149
	v_fmac_f32_e32 v143, v137, v150
	v_fmac_f32_e32 v144, v137, v151
	v_fmac_f32_e32 v145, v137, v156
	ds_read2_b32 v[136:137], v155 offset0:224 offset1:240
	v_lshlrev_b32_e32 v138, 16, v116
	v_and_b32_e32 v139, 0xffff0000, v116
	v_lshlrev_b32_e32 v148, 16, v117
	v_and_b32_e32 v149, 0xffff0000, v117
	v_lshlrev_b32_e32 v150, 16, v118
	v_and_b32_e32 v151, 0xffff0000, v118
	v_lshlrev_b32_e32 v156, 16, v119
	v_and_b32_e32 v157, 0xffff0000, v119
	s_waitcnt lgkmcnt(0)
	v_fmac_f32_e32 v146, v136, v138
	v_fmac_f32_e32 v147, v136, v139
	v_fmac_f32_e32 v140, v136, v148
	v_fmac_f32_e32 v141, v136, v149
	v_fmac_f32_e32 v142, v136, v150
	v_fmac_f32_e32 v143, v136, v151
	v_fmac_f32_e32 v144, v136, v156
	v_fmac_f32_e32 v145, v136, v157
	v_lshlrev_b32_e32 v136, 16, v124
	v_and_b32_e32 v138, 0xffff0000, v124
	v_lshlrev_b32_e32 v139, 16, v125
	v_and_b32_e32 v148, 0xffff0000, v125
	v_lshlrev_b32_e32 v149, 16, v126
	v_and_b32_e32 v150, 0xffff0000, v126
	v_lshlrev_b32_e32 v151, 16, v127
	v_and_b32_e32 v156, 0xffff0000, v127
	s_ashr_i32 s10, s15, 6
	v_fmac_f32_e32 v146, v137, v136
	v_fmac_f32_e32 v147, v137, v138
	v_fmac_f32_e32 v140, v137, v139
	v_fmac_f32_e32 v141, v137, v148
	v_fmac_f32_e32 v142, v137, v149
	v_fmac_f32_e32 v143, v137, v150
	v_fmac_f32_e32 v144, v137, v151
	v_fmac_f32_e32 v145, v137, v156
	v_cvt_pk_bf16_f32 v136, v146, v147
	v_cvt_pk_bf16_f32 v137, v140, v141
	v_cvt_pk_bf16_f32 v138, v142, v143
	v_cvt_pk_bf16_f32 v139, v144, v145
	s_cmp_gt_i32 s10, s14
	v_and_b32_e32 v151, 0xffff0000, v137
	v_lshlrev_b32_e32 v156, 16, v138
	v_and_b32_e32 v157, 0xffff0000, v138
	v_lshlrev_b32_e32 v148, 16, v136
	v_and_b32_e32 v149, 0xffff0000, v136
	v_lshlrev_b32_e32 v150, 16, v137
	v_lshlrev_b32_e32 v158, 16, v139
	v_and_b32_e32 v159, 0xffff0000, v139
	v_sub_f32_e32 v141, v141, v151
	v_sub_f32_e32 v142, v142, v156
	v_sub_f32_e32 v143, v143, v157
	v_sub_f32_e32 v146, v146, v148
	v_sub_f32_e32 v147, v147, v149
	v_sub_f32_e32 v148, v140, v150
	v_sub_f32_e32 v144, v144, v158
	v_sub_f32_e32 v145, v145, v159
	v_cvt_pk_bf16_f32 v140, v146, v147
	v_cvt_pk_bf16_f32 v141, v148, v141
	v_cvt_pk_bf16_f32 v142, v142, v143
	v_cvt_pk_bf16_f32 v143, v144, v145
	s_cbranch_scc1 .LBB0_290
	s_lshl_b64 s[4:5], s[8:9], 20
	v_and_b32_e32 v144, 63, v152
	s_add_u32 s4, s88, s4
	s_addc_u32 s5, s89, s5
	v_lshlrev_b32_e32 v160, 4, v144
	s_ashr_i32 s11, s10, 31
	v_lshl_add_u64 v[162:163], s[4:5], 0, v[160:161]
	s_lshl_b64 s[4:5], s[10:11], 11
	v_lshl_add_u64 v[144:145], v[162:163], 0, s[4:5]
	global_load_dwordx4 v[148:151], v[144:145], off
	s_nop 0
	global_load_dwordx4 v[144:147], v[144:145], off offset:1024
	v_add_u32_e32 v186, 0xa200, v154
	v_add_u32_e32 v187, 0xa240, v154
	v_add_u32_e32 v188, 0xa280, v154
	v_add_u32_e32 v189, 0xa2c0, v154
	v_add_u32_e32 v190, 0xa300, v154
	v_add_u32_e32 v191, 0xa340, v154
	v_add_u32_e32 v192, 0xa380, v154
	v_add_u32_e32 v156, 0xa040, v154
	v_add_u32_e32 v157, 0xa080, v154
	v_add_u32_e32 v158, 0xa0c0, v154
	v_add_u32_e32 v159, 0xa100, v154
	v_add_u32_e32 v160, 0xa140, v154
	v_add_u32_e32 v164, 0xa180, v154
	v_add_u32_e32 v165, 0xa1c0, v154
	v_add_u32_e32 v154, 0xa3c0, v154
	ds_read_b32 v178, v155
	ds_read_b32 v179, v156
	ds_read_b32 v180, v157
	ds_read_b32 v181, v158
	ds_read_b32 v182, v159
	ds_read_b32 v183, v160
	ds_read_b32 v184, v164
	ds_read_b32 v185, v165
	ds_read_b32 v186, v186
	ds_read_b32 v187, v187
	ds_read_b32 v188, v188
	ds_read_b32 v189, v189
	ds_read_b32 v190, v190
	ds_read_b32 v191, v191
	ds_read_b32 v192, v192
	ds_read_b32 v193, v154
	s_lshl_b32 s4, s10, 4
	s_ashr_i32 s5, s4, 31
	s_lshl_b64 s[4:5], s[4:5], 2
	v_and_b32_e32 v152, 48, v152
	s_add_u32 s4, s92, s4
	v_lshl_or_b32 v160, v153, 15, v152
	s_addc_u32 s5, s93, s5
	v_lshl_add_u64 v[164:165], s[4:5], 0, v[160:161]
	s_mov_b32 s12, s10
	s_cmp_lt_u32 s10, 4
	s_cbranch_scc1 .Lidx_noprio
	s_setprio 1
.Lidx_noprio:
	s_waitcnt vmcnt(0) lgkmcnt(0)

; __device__ __forceinline__ void dsa_tile(const Params& p, unsigned char* smem, int tile) {
;     ...
;     __syncthreads();
;     int* myidx = (int*)smem + wid * 256;
;     float* pl = (float*)(smem + 8192) + wid * 1024;
;     unsigned* hist = (unsigned*)(smem + 41984) + wid * 2048;
;     bf16_t* yb = (bf16_t*)(p.ws + WS_Y);
; #pragma unroll 1
;     for (int qi = wid * 2; qi < wid * 2 + 2; ++qi) {
.LBB0_290:
	s_setprio 0
	s_lshl_b32 s4, s10, 10
	s_add_i32 s96, s4, 0
	s_mul_i32 s4, s10, 0x1c00
	s_add_i32 s97, s96, s4
	s_lshl_b32 s58, s10, 1
	s_lshl_b64 s[4:5], s[8:9], 22
	s_add_u32 s74, s90, s4
	s_addc_u32 s71, s91, s5
	s_or_b32 s54, s58, 1
	s_barrier
	s_branch .LBB0_292
